# plus: K-loop LDS-DMA address math moved off the VALU (immediate offset with M0 compensation, SGPR-base forms, single LDS read base)
# speedup vs baseline: 1.0161x; 1.0024x over previous
; #define PG8_STAGE(bufoff, gbase, off, q) do { \
;         __builtin_amdgcn_global_load_lds((const unsigned*)((const char*)(gbase) + (off)), (LAS unsigned*)(lds + (bufoff) + ldsw), 16, 0, 0); \
;         __builtin_amdgcn_global_load_lds((const unsigned*)((const char*)(gbase) + (q) + (off)), (LAS unsigned*)(lds + (bufoff) + ldsw + 8192), 16, 0, 0); } while (0)
; #define PG8_LDA(dst, b, h) do { _Pragma("unroll") for (int m = 0; m < 4; ++m) _Pragma("unroll") for (int k = 0; k < 2; ++k) dst[m][k] = *(const LAS bf16x8*)(lds + PG8_SA(b, h) + aoff + m * 2048 + k * 1024); } while (0)
; #define PG8_LDB(dst, b, h) do { _Pragma("unroll") for (int n = 0; n < 2; ++n) _Pragma("unroll") for (int k = 0; k < 2; ++k) dst[n][k] = *(const LAS bf16x8*)(lds + PG8_SB(b, h) + boff + n * 2048 + k * 1024); } while (0)
; #define PG8_MMA(ai, bj, At, Bt) do { __builtin_amdgcn_s_setprio(1); _Pragma("unroll") for (int m = 0; m < 4; ++m) _Pragma("unroll") for (int n = 0; n < 2; ++n) _Pragma("unroll") for (int k = 0; k < 2; ++k) \
;         acc[ai][bj][m][n] = __builtin_amdgcn_mfma_f32_16x16x32_bf16(Bt[n][k], At[m][k], acc[ai][bj][m][n], 0, 0, 0); __builtin_amdgcn_s_setprio(0); } while (0)
; #define PG8_WAIT_V(n) asm volatile("s_waitcnt vmcnt(" #n ")" ::: "memory")
; #define PG8_WAIT_L(n) asm volatile("s_waitcnt lgkmcnt(" #n ")" ::: "memory")
; #define PG8_BAR __builtin_amdgcn_s_barrier()
; #define PG8_SCHED __builtin_amdgcn_sched_barrier(0)
; template <class Epi, class Sched>
; __device__ __forceinline__ void gemm_phase(LAS unsigned char* lds, const int tid, const Sched& S, const Epi& E) {
;     ...
;             PG8_LDB(B0, 0, 0); PG8_LDB(B1, 0, 1); PG8_SCHED; PG8_LDA(At, 0, 0); PG8_STAGE(PG8_SA(1, 1), a1 + hA, offA, qA);
;             PG8_WAIT_V(8); PG8_WAIT_L(0); PG8_BAR; PG8_MMA(0, 0, At, B0); PG8_MMA(0, 1, At, B1); PG8_BAR; PG8_SCHED;
;             PG8_LDA(At, 0, 1); PG8_STAGE(PG8_SB(0, 0), b2, oB2, qB2); PG8_STAGE(PG8_SB(0, 1), b2 + hB2, oB2, qB2); PG8_STAGE(PG8_SA(0, 0), a2, oA2, qA2);
;             PG8_WAIT_V(8); PG8_WAIT_L(0); PG8_BAR; PG8_MMA(1, 0, At, B0); PG8_MMA(1, 1, At, B1); PG8_BAR; PG8_SCHED;
.LBB0_175:
	s_or_b32 vcc_lo, s17, 1
	s_mov_b32 vcc_hi, s21
	s_lshl_b64 s[10:11], vcc, 7
	s_add_u32 s17, s40, s6
	s_addc_u32 vcc_lo, s41, s7
	s_and_b64 s[6:7], exec, s[62:63]
	s_cselect_b32 vcc_hi, s82, vcc_lo
	s_cselect_b32 vcc_lo, s48, s17
	s_add_i32 s17, 0, 0x10000
	v_add_u32_e32 v133, s17, v147
	s_add_i32 s62, 0, 0x14000
	ds_read_b128 v[140:143], v133
	ds_read_b128 v[150:153], v133 offset:1024
	ds_read_b128 v[154:157], v133 offset:2048
	ds_read_b128 v[158:161], v133 offset:3072
	ds_read_b128 v[186:189], v133 offset:16384
	ds_read_b128 v[190:193], v133 offset:17408
	ds_read_b128 v[194:197], v133 offset:18432
	ds_read_b128 v[198:201], v133 offset:19456
	s_add_u32 s6, s68, s10
	s_addc_u32 s7, s16, s11
	s_add_i32 m0, s54, 0xc000
	ds_read_b128 v[202:205], v184
	ds_read_b128 v[206:209], v184 offset:1024
	ds_read_b128 v[210:213], v184 offset:2048
	ds_read_b128 v[214:217], v184 offset:3072
	ds_read_b128 v[218:221], v184 offset:4096
	ds_read_b128 v[222:225], v184 offset:5120
	ds_read_b128 v[226:229], v184 offset:6144
	ds_read_b128 v[230:233], v184 offset:7168
	global_load_lds_dwordx4 v134, s[6:7]
	s_add_u32 s6, s6, s66
	s_addc_u32 s7, s7, s67
	s_add_i32 m0, s54, 0xe000
	s_nop 0
	global_load_lds_dwordx4 v134, s[6:7]
	s_waitcnt vmcnt(8)
	s_waitcnt lgkmcnt(0)
	s_barrier
	s_setprio 1
	s_waitcnt lgkmcnt(0)
	v_mfma_f32_16x16x32_bf16 v[126:129], v[140:143], v[202:205], v[126:129]
	v_mfma_f32_16x16x32_bf16 v[122:125], v[154:157], v[202:205], v[122:125]
	v_mfma_f32_16x16x32_bf16 v[110:113], v[140:143], v[210:213], v[110:113]
	v_mfma_f32_16x16x32_bf16 v[106:109], v[154:157], v[210:213], v[106:109]
	v_mfma_f32_16x16x32_bf16 v[94:97], v[140:143], v[218:221], v[94:97]
	v_mfma_f32_16x16x32_bf16 v[90:93], v[154:157], v[218:221], v[90:93]
	v_mfma_f32_16x16x32_bf16 v[78:81], v[140:143], v[226:229], v[78:81]
	v_mfma_f32_16x16x32_bf16 v[74:77], v[154:157], v[226:229], v[74:77]
	v_mfma_f32_16x16x32_bf16 v[126:129], v[150:153], v[206:209], v[126:129]
	v_mfma_f32_16x16x32_bf16 v[122:125], v[158:161], v[206:209], v[122:125]
	v_mfma_f32_16x16x32_bf16 v[110:113], v[150:153], v[214:217], v[110:113]
	v_mfma_f32_16x16x32_bf16 v[106:109], v[158:161], v[214:217], v[106:109]
	v_mfma_f32_16x16x32_bf16 v[94:97], v[150:153], v[222:225], v[94:97]
	v_mfma_f32_16x16x32_bf16 v[90:93], v[158:161], v[222:225], v[90:93]
	v_mfma_f32_16x16x32_bf16 v[78:81], v[150:153], v[230:233], v[78:81]
	v_mfma_f32_16x16x32_bf16 v[74:77], v[158:161], v[230:233], v[74:77]
	s_setprio 0
	s_setprio 1
	v_mfma_f32_16x16x32_bf16 v[118:121], v[186:189], v[202:205], v[118:121]
	v_mfma_f32_16x16x32_bf16 v[114:117], v[194:197], v[202:205], v[114:117]
	v_mfma_f32_16x16x32_bf16 v[102:105], v[186:189], v[210:213], v[102:105]
	v_mfma_f32_16x16x32_bf16 v[98:101], v[194:197], v[210:213], v[98:101]
	v_mfma_f32_16x16x32_bf16 v[86:89], v[186:189], v[218:221], v[86:89]
	v_mfma_f32_16x16x32_bf16 v[82:85], v[194:197], v[218:221], v[82:85]
	v_mfma_f32_16x16x32_bf16 v[70:73], v[186:189], v[226:229], v[70:73]
	v_mfma_f32_16x16x32_bf16 v[66:69], v[194:197], v[226:229], v[66:69]
	v_mfma_f32_16x16x32_bf16 v[118:121], v[190:193], v[206:209], v[118:121]
	v_mfma_f32_16x16x32_bf16 v[114:117], v[198:201], v[206:209], v[114:117]
	v_mfma_f32_16x16x32_bf16 v[102:105], v[190:193], v[214:217], v[102:105]
	v_mfma_f32_16x16x32_bf16 v[98:101], v[198:201], v[214:217], v[98:101]
	v_mfma_f32_16x16x32_bf16 v[86:89], v[190:193], v[222:225], v[86:89]
	v_mfma_f32_16x16x32_bf16 v[82:85], v[198:201], v[222:225], v[82:85]
	v_mfma_f32_16x16x32_bf16 v[70:73], v[190:193], v[230:233], v[70:73]
	v_mfma_f32_16x16x32_bf16 v[66:69], v[198:201], v[230:233], v[66:69]
	s_setprio 0
	s_barrier
	s_add_i32 s10, s17, s47
	s_ashr_i32 s11, s73, 31
	s_mov_b32 m0, s10
	s_add_u32 s6, s28, s73
	ds_read_b128 v[202:205], v184 offset:16384
	ds_read_b128 v[206:209], v184 offset:17408
	ds_read_b128 v[210:213], v184 offset:18432
	ds_read_b128 v[214:217], v184 offset:19456
	ds_read_b128 v[218:221], v184 offset:20480
	ds_read_b128 v[222:225], v184 offset:21504
	ds_read_b128 v[226:229], v184 offset:22528
	ds_read_b128 v[230:233], v184 offset:23552
	global_load_lds_dwordx4 v0, s[28:29]
	s_addc_u32 s7, s29, s11
	s_add_i32 m0, s10, 0x2000
	v_lshl_add_u64 v[162:163], s[6:7], 0, v[0:1]
	global_load_lds_dwordx4 v0, s[6:7]
	s_ashr_i32 s7, s19, 31
	s_add_u32 s6, s28, s19
	s_addc_u32 s7, s29, s7
	s_add_i32 s10, s62, s47
	s_mov_b32 m0, s10
	v_lshl_add_u64 v[234:235], s[6:7], 0, v[0:1]
	global_load_lds_dwordx4 v0, s[6:7]
	s_add_u32 s6, s6, s73
	s_addc_u32 s7, s7, s11
	s_add_i32 m0, s10, 0x2000
	v_lshl_add_u64 v[236:237], s[6:7], 0, v[0:1]
	global_load_lds_dwordx4 v0, s[6:7]
	s_add_u32 s6, vcc_lo, s64
	v_lshl_add_u64 v[238:239], vcc, 0, v[136:137]
	s_mov_b32 m0, s54
	s_addc_u32 s7, vcc_hi, s65
	global_load_lds_dwordx4 v[238:239], off
	v_lshl_add_u64 v[240:241], s[6:7], 0, v[136:137]
	s_mov_b32 m0, s55
	v_lshl_add_u64 v[144:145], s[28:29], 0, v[0:1]
	global_load_lds_dwordx4 v[240:241], off
	s_waitcnt vmcnt(8)
	s_waitcnt lgkmcnt(0)
	s_barrier
; #define PG8_STAGE(bufoff, gbase, off, q) do { \
;         __builtin_amdgcn_global_load_lds((const unsigned*)((const char*)(gbase) + (off)), (LAS unsigned*)(lds + (bufoff) + ldsw), 16, 0, 0); \
;         __builtin_amdgcn_global_load_lds((const unsigned*)((const char*)(gbase) + (q) + (off)), (LAS unsigned*)(lds + (bufoff) + ldsw + 8192), 16, 0, 0); } while (0)
; #define PG8_LDA(dst, b, h) do { _Pragma("unroll") for (int m = 0; m < 4; ++m) _Pragma("unroll") for (int k = 0; k < 2; ++k) dst[m][k] = *(const LAS bf16x8*)(lds + PG8_SA(b, h) + aoff + m * 2048 + k * 1024); } while (0)
; #define PG8_LDB(dst, b, h) do { _Pragma("unroll") for (int n = 0; n < 2; ++n) _Pragma("unroll") for (int k = 0; k < 2; ++k) dst[n][k] = *(const LAS bf16x8*)(lds + PG8_SB(b, h) + boff + n * 2048 + k * 1024); } while (0)
; #define PG8_MMA(ai, bj, At, Bt) do { __builtin_amdgcn_s_setprio(1); _Pragma("unroll") for (int m = 0; m < 4; ++m) _Pragma("unroll") for (int n = 0; n < 2; ++n) _Pragma("unroll") for (int k = 0; k < 2; ++k) \
;         acc[ai][bj][m][n] = __builtin_amdgcn_mfma_f32_16x16x32_bf16(Bt[n][k], At[m][k], acc[ai][bj][m][n], 0, 0, 0); __builtin_amdgcn_s_setprio(0); } while (0)
; #define PG8_WAIT_V(n) asm volatile("s_waitcnt vmcnt(" #n ")" ::: "memory")
; #define PG8_WAIT_L(n) asm volatile("s_waitcnt lgkmcnt(" #n ")" ::: "memory")
; #define PG8_BAR __builtin_amdgcn_s_barrier()
; #define PG8_SCHED __builtin_amdgcn_sched_barrier(0)
; template <class Epi, class Sched>
; __device__ __forceinline__ void gemm_phase(LAS unsigned char* lds, const int tid, const Sched& S, const Epi& E) {
;     ...
;             PG8_WAIT_V(8); PG8_WAIT_L(0); PG8_BAR; PG8_MMA(1, 0, At, B0); PG8_MMA(1, 1, At, B1); PG8_BAR; PG8_SCHED;
;             PG8_LDB(B0, 1, 0); PG8_LDB(B1, 1, 1); PG8_SCHED; PG8_LDA(At, 1, 0); PG8_STAGE(PG8_SA(0, 1), a2 + hA2, oA2, qA2);
;             PG8_WAIT_V(8); PG8_WAIT_L(0); PG8_BAR; PG8_MMA(0, 0, At, B0); PG8_MMA(0, 1, At, B1); PG8_BAR; PG8_SCHED;
	s_setprio 1
	s_waitcnt lgkmcnt(0)
	v_mfma_f32_16x16x32_bf16 v[62:65], v[140:143], v[202:205], v[62:65]
	v_mfma_f32_16x16x32_bf16 v[58:61], v[154:157], v[202:205], v[58:61]
	v_mfma_f32_16x16x32_bf16 v[46:49], v[140:143], v[210:213], v[46:49]
	v_mfma_f32_16x16x32_bf16 v[42:45], v[154:157], v[210:213], v[42:45]
	v_mfma_f32_16x16x32_bf16 v[30:33], v[140:143], v[218:221], v[30:33]
	v_mfma_f32_16x16x32_bf16 v[26:29], v[154:157], v[218:221], v[26:29]
	v_mfma_f32_16x16x32_bf16 v[14:17], v[140:143], v[226:229], v[14:17]
	v_mfma_f32_16x16x32_bf16 v[10:13], v[154:157], v[226:229], v[10:13]
	v_mfma_f32_16x16x32_bf16 v[62:65], v[150:153], v[206:209], v[62:65]
	v_mfma_f32_16x16x32_bf16 v[58:61], v[158:161], v[206:209], v[58:61]
	v_mfma_f32_16x16x32_bf16 v[46:49], v[150:153], v[214:217], v[46:49]
	v_mfma_f32_16x16x32_bf16 v[42:45], v[158:161], v[214:217], v[42:45]
	v_mfma_f32_16x16x32_bf16 v[30:33], v[150:153], v[222:225], v[30:33]
	v_mfma_f32_16x16x32_bf16 v[26:29], v[158:161], v[222:225], v[26:29]
	v_mfma_f32_16x16x32_bf16 v[14:17], v[150:153], v[230:233], v[14:17]
	v_mfma_f32_16x16x32_bf16 v[10:13], v[158:161], v[230:233], v[10:13]
	s_setprio 0
	s_setprio 1
	v_mfma_f32_16x16x32_bf16 v[54:57], v[186:189], v[202:205], v[54:57]
	v_mfma_f32_16x16x32_bf16 v[50:53], v[194:197], v[202:205], v[50:53]
	v_mfma_f32_16x16x32_bf16 v[38:41], v[186:189], v[210:213], v[38:41]
	v_mfma_f32_16x16x32_bf16 v[34:37], v[194:197], v[210:213], v[34:37]
	v_mfma_f32_16x16x32_bf16 v[22:25], v[186:189], v[218:221], v[22:25]
	v_mfma_f32_16x16x32_bf16 v[18:21], v[194:197], v[218:221], v[18:21]
	v_mfma_f32_16x16x32_bf16 v[6:9], v[186:189], v[226:229], v[6:9]
	v_mfma_f32_16x16x32_bf16 v[2:5], v[194:197], v[226:229], v[2:5]
	v_mfma_f32_16x16x32_bf16 v[54:57], v[190:193], v[206:209], v[54:57]
	v_mfma_f32_16x16x32_bf16 v[50:53], v[198:201], v[206:209], v[50:53]
	v_mfma_f32_16x16x32_bf16 v[38:41], v[190:193], v[214:217], v[38:41]
	v_mfma_f32_16x16x32_bf16 v[34:37], v[198:201], v[214:217], v[34:37]
	v_mfma_f32_16x16x32_bf16 v[22:25], v[190:193], v[222:225], v[22:25]
	v_mfma_f32_16x16x32_bf16 v[18:21], v[198:201], v[222:225], v[18:21]
	v_mfma_f32_16x16x32_bf16 v[6:9], v[190:193], v[230:233], v[6:9]
	v_mfma_f32_16x16x32_bf16 v[2:5], v[198:201], v[230:233], v[2:5]
	s_setprio 0
	s_barrier
	s_add_i32 s10, 0, 0x18000
	s_add_i32 s11, 0, 0x1c000
	ds_read_b128 v[140:143], v133 offset:32768
	ds_read_b128 v[150:153], v133 offset:33792
	ds_read_b128 v[154:157], v133 offset:34816
	ds_read_b128 v[158:161], v133 offset:35840
	ds_read_b128 v[186:189], v133 offset:49152
	ds_read_b128 v[190:193], v133 offset:50176
	ds_read_b128 v[194:197], v133 offset:51200
	ds_read_b128 v[198:201], v133 offset:52224
	s_add_u32 s6, vcc_lo, s58
	s_addc_u32 s7, vcc_hi, s59
	s_mov_b32 m0, s91
	ds_read_b128 v[202:205], v184 offset:32768
	ds_read_b128 v[206:209], v184 offset:33792
	ds_read_b128 v[210:213], v184 offset:34816
	ds_read_b128 v[214:217], v184 offset:35840
	ds_read_b128 v[218:221], v184 offset:36864
	ds_read_b128 v[222:225], v184 offset:37888
	ds_read_b128 v[226:229], v184 offset:38912
	ds_read_b128 v[230:233], v184 offset:39936
	global_load_lds_dwordx4 v136, s[6:7]
	s_add_u32 s6, s6, s64
	s_addc_u32 s7, s7, s65
	s_mov_b32 m0, s93
	s_nop 0
	global_load_lds_dwordx4 v136, s[6:7]
	s_waitcnt vmcnt(8)
	s_waitcnt lgkmcnt(0)
	s_barrier
	s_setprio 1
	s_waitcnt lgkmcnt(0)
	v_mfma_f32_16x16x32_bf16 v[126:129], v[140:143], v[202:205], v[126:129]
	v_mfma_f32_16x16x32_bf16 v[122:125], v[154:157], v[202:205], v[122:125]
	v_mfma_f32_16x16x32_bf16 v[110:113], v[140:143], v[210:213], v[110:113]
	v_mfma_f32_16x16x32_bf16 v[106:109], v[154:157], v[210:213], v[106:109]
	v_mfma_f32_16x16x32_bf16 v[94:97], v[140:143], v[218:221], v[94:97]
	v_mfma_f32_16x16x32_bf16 v[90:93], v[154:157], v[218:221], v[90:93]
	v_mfma_f32_16x16x32_bf16 v[78:81], v[140:143], v[226:229], v[78:81]
	v_mfma_f32_16x16x32_bf16 v[74:77], v[154:157], v[226:229], v[74:77]
	v_mfma_f32_16x16x32_bf16 v[126:129], v[150:153], v[206:209], v[126:129]
	v_mfma_f32_16x16x32_bf16 v[122:125], v[158:161], v[206:209], v[122:125]
	v_mfma_f32_16x16x32_bf16 v[110:113], v[150:153], v[214:217], v[110:113]
	v_mfma_f32_16x16x32_bf16 v[106:109], v[158:161], v[214:217], v[106:109]
	v_mfma_f32_16x16x32_bf16 v[94:97], v[150:153], v[222:225], v[94:97]
	v_mfma_f32_16x16x32_bf16 v[90:93], v[158:161], v[222:225], v[90:93]
	v_mfma_f32_16x16x32_bf16 v[78:81], v[150:153], v[230:233], v[78:81]
	v_mfma_f32_16x16x32_bf16 v[74:77], v[158:161], v[230:233], v[74:77]
	s_setprio 0
	s_setprio 1
	v_mfma_f32_16x16x32_bf16 v[118:121], v[186:189], v[202:205], v[118:121]
	v_mfma_f32_16x16x32_bf16 v[114:117], v[194:197], v[202:205], v[114:117]
	v_mfma_f32_16x16x32_bf16 v[102:105], v[186:189], v[210:213], v[102:105]
	v_mfma_f32_16x16x32_bf16 v[98:101], v[194:197], v[210:213], v[98:101]
	v_mfma_f32_16x16x32_bf16 v[86:89], v[186:189], v[218:221], v[86:89]
	v_mfma_f32_16x16x32_bf16 v[82:85], v[194:197], v[218:221], v[82:85]
	v_mfma_f32_16x16x32_bf16 v[70:73], v[186:189], v[226:229], v[70:73]
	v_mfma_f32_16x16x32_bf16 v[66:69], v[194:197], v[226:229], v[66:69]
	v_mfma_f32_16x16x32_bf16 v[118:121], v[190:193], v[206:209], v[118:121]
	v_mfma_f32_16x16x32_bf16 v[114:117], v[198:201], v[206:209], v[114:117]
	v_mfma_f32_16x16x32_bf16 v[102:105], v[190:193], v[214:217], v[102:105]
	v_mfma_f32_16x16x32_bf16 v[98:101], v[198:201], v[214:217], v[98:101]
	v_mfma_f32_16x16x32_bf16 v[86:89], v[190:193], v[222:225], v[86:89]
	v_mfma_f32_16x16x32_bf16 v[82:85], v[198:201], v[222:225], v[82:85]
	v_mfma_f32_16x16x32_bf16 v[70:73], v[190:193], v[230:233], v[70:73]
	v_mfma_f32_16x16x32_bf16 v[66:69], v[198:201], v[230:233], v[66:69]
	s_setprio 0
	s_barrier
; #define PG8_STAGE(bufoff, gbase, off, q) do { \
;         __builtin_amdgcn_global_load_lds((const unsigned*)((const char*)(gbase) + (off)), (LAS unsigned*)(lds + (bufoff) + ldsw), 16, 0, 0); \
;         __builtin_amdgcn_global_load_lds((const unsigned*)((const char*)(gbase) + (q) + (off)), (LAS unsigned*)(lds + (bufoff) + ldsw + 8192), 16, 0, 0); } while (0)
; #define PG8_LDA(dst, b, h) do { _Pragma("unroll") for (int m = 0; m < 4; ++m) _Pragma("unroll") for (int k = 0; k < 2; ++k) dst[m][k] = *(const LAS bf16x8*)(lds + PG8_SA(b, h) + aoff + m * 2048 + k * 1024); } while (0)
; #define PG8_MMA(ai, bj, At, Bt) do { __builtin_amdgcn_s_setprio(1); _Pragma("unroll") for (int m = 0; m < 4; ++m) _Pragma("unroll") for (int n = 0; n < 2; ++n) _Pragma("unroll") for (int k = 0; k < 2; ++k) \
;         acc[ai][bj][m][n] = __builtin_amdgcn_mfma_f32_16x16x32_bf16(Bt[n][k], At[m][k], acc[ai][bj][m][n], 0, 0, 0); __builtin_amdgcn_s_setprio(0); } while (0)
; #define PG8_WAIT_V(n) asm volatile("s_waitcnt vmcnt(" #n ")" ::: "memory")
; #define PG8_WAIT_L(n) asm volatile("s_waitcnt lgkmcnt(" #n ")" ::: "memory")
; #define PG8_BAR __builtin_amdgcn_s_barrier()
; #define PG8_SCHED __builtin_amdgcn_sched_barrier(0)
; template <class Epi, class Sched>
; __device__ __forceinline__ void gemm_phase(LAS unsigned char* lds, const int tid, const Sched& S, const Epi& E) {
;     ...
;             PG8_LDA(At, 1, 1); PG8_STAGE(PG8_SB(1, 0), b3, oB2, qB2); PG8_STAGE(PG8_SB(1, 1), b3 + hB2, oB2, qB2); PG8_STAGE(PG8_SA(1, 0), a3, oA2, qA2);
;             PG8_WAIT_V(8); PG8_WAIT_L(0); PG8_BAR; PG8_MMA(1, 0, At, B0); PG8_MMA(1, 1, At, B1); PG8_BAR; PG8_SCHED;
;         }
	s_add_i32 s6, s10, s47
	s_add_i32 m0, s6, 0xffffff80
	ds_read_b128 v[202:205], v184 offset:49152
	ds_read_b128 v[206:209], v184 offset:50176
	ds_read_b128 v[210:213], v184 offset:51200
	ds_read_b128 v[214:217], v184 offset:52224
	ds_read_b128 v[218:221], v184 offset:53248
	ds_read_b128 v[222:225], v184 offset:54272
	ds_read_b128 v[226:229], v184 offset:55296
	ds_read_b128 v[230:233], v184 offset:56320
	global_load_lds_dwordx4 v[144:145], off offset:128
	s_add_i32 m0, s6, 0x1f80
	s_add_i32 s6, s11, s47
	global_load_lds_dwordx4 v[162:163], off offset:128
	s_add_i32 m0, s6, 0xffffff80
	s_nop 0
	global_load_lds_dwordx4 v[234:235], off offset:128
	s_add_i32 m0, s6, 0x1f80
	s_nop 0
	global_load_lds_dwordx4 v[236:237], off offset:128
	s_add_i32 m0, s77, 0xffffff80
	s_nop 0
	global_load_lds_dwordx4 v[238:239], off offset:128
	s_add_i32 m0, s88, 0xffffff80
	s_nop 0
	global_load_lds_dwordx4 v[240:241], off offset:128
	s_waitcnt vmcnt(8)
	s_waitcnt lgkmcnt(0)
	s_barrier
	s_setprio 1
	s_waitcnt lgkmcnt(0)
	v_mfma_f32_16x16x32_bf16 v[62:65], v[140:143], v[202:205], v[62:65]
	v_mfma_f32_16x16x32_bf16 v[58:61], v[154:157], v[202:205], v[58:61]
	v_mfma_f32_16x16x32_bf16 v[46:49], v[140:143], v[210:213], v[46:49]
	v_mfma_f32_16x16x32_bf16 v[42:45], v[154:157], v[210:213], v[42:45]
	v_mfma_f32_16x16x32_bf16 v[30:33], v[140:143], v[218:221], v[30:33]
	v_mfma_f32_16x16x32_bf16 v[26:29], v[154:157], v[218:221], v[26:29]
	v_mfma_f32_16x16x32_bf16 v[14:17], v[140:143], v[226:229], v[14:17]
	v_mfma_f32_16x16x32_bf16 v[10:13], v[154:157], v[226:229], v[10:13]
	v_mfma_f32_16x16x32_bf16 v[62:65], v[150:153], v[206:209], v[62:65]
	v_mfma_f32_16x16x32_bf16 v[58:61], v[158:161], v[206:209], v[58:61]
	v_mfma_f32_16x16x32_bf16 v[46:49], v[150:153], v[214:217], v[46:49]
	v_mfma_f32_16x16x32_bf16 v[42:45], v[158:161], v[214:217], v[42:45]
	v_mfma_f32_16x16x32_bf16 v[30:33], v[150:153], v[222:225], v[30:33]
	v_mfma_f32_16x16x32_bf16 v[26:29], v[158:161], v[222:225], v[26:29]
	v_mfma_f32_16x16x32_bf16 v[14:17], v[150:153], v[230:233], v[14:17]
	v_mfma_f32_16x16x32_bf16 v[10:13], v[158:161], v[230:233], v[10:13]
	s_setprio 0
	s_setprio 1
	v_mfma_f32_16x16x32_bf16 v[54:57], v[186:189], v[202:205], v[54:57]
	v_mfma_f32_16x16x32_bf16 v[50:53], v[194:197], v[202:205], v[50:53]
	v_mfma_f32_16x16x32_bf16 v[38:41], v[186:189], v[210:213], v[38:41]
	v_mfma_f32_16x16x32_bf16 v[34:37], v[194:197], v[210:213], v[34:37]
	v_mfma_f32_16x16x32_bf16 v[22:25], v[186:189], v[218:221], v[22:25]
	v_mfma_f32_16x16x32_bf16 v[18:21], v[194:197], v[218:221], v[18:21]
	v_mfma_f32_16x16x32_bf16 v[6:9], v[186:189], v[226:229], v[6:9]
	v_mfma_f32_16x16x32_bf16 v[2:5], v[194:197], v[226:229], v[2:5]
	v_mfma_f32_16x16x32_bf16 v[54:57], v[190:193], v[206:209], v[54:57]
	v_mfma_f32_16x16x32_bf16 v[50:53], v[198:201], v[206:209], v[50:53]
	v_mfma_f32_16x16x32_bf16 v[38:41], v[190:193], v[214:217], v[38:41]
	v_mfma_f32_16x16x32_bf16 v[34:37], v[198:201], v[214:217], v[34:37]
	v_mfma_f32_16x16x32_bf16 v[22:25], v[190:193], v[222:225], v[22:25]
	v_mfma_f32_16x16x32_bf16 v[18:21], v[198:201], v[222:225], v[18:21]
	v_mfma_f32_16x16x32_bf16 v[6:9], v[190:193], v[230:233], v[6:9]
	v_mfma_f32_16x16x32_bf16 v[2:5], v[198:201], v[230:233], v[2:5]
	s_setprio 0
	s_barrier
	s_cmp_ge_i32 s20, s37
	s_cbranch_scc1 .LBB0_177
	s_mov_b32 s17, s20
	s_branch .LBB0_173

; #define PG8_STAGE(bufoff, gbase, off, q) do { \
;         __builtin_amdgcn_global_load_lds((const unsigned*)((const char*)(gbase) + (off)), (LAS unsigned*)(lds + (bufoff) + ldsw), 16, 0, 0); \
;         __builtin_amdgcn_global_load_lds((const unsigned*)((const char*)(gbase) + (q) + (off)), (LAS unsigned*)(lds + (bufoff) + ldsw + 8192), 16, 0, 0); } while (0)
; #define PG8_LDA(dst, b, h) do { _Pragma("unroll") for (int m = 0; m < 4; ++m) _Pragma("unroll") for (int k = 0; k < 2; ++k) dst[m][k] = *(const LAS bf16x8*)(lds + PG8_SA(b, h) + aoff + m * 2048 + k * 1024); } while (0)
; #define PG8_LDB(dst, b, h) do { _Pragma("unroll") for (int n = 0; n < 2; ++n) _Pragma("unroll") for (int k = 0; k < 2; ++k) dst[n][k] = *(const LAS bf16x8*)(lds + PG8_SB(b, h) + boff + n * 2048 + k * 1024); } while (0)
; #define PG8_MMA(ai, bj, At, Bt) do { __builtin_amdgcn_s_setprio(1); _Pragma("unroll") for (int m = 0; m < 4; ++m) _Pragma("unroll") for (int n = 0; n < 2; ++n) _Pragma("unroll") for (int k = 0; k < 2; ++k) \
;         acc[ai][bj][m][n] = __builtin_amdgcn_mfma_f32_16x16x32_bf16(Bt[n][k], At[m][k], acc[ai][bj][m][n], 0, 0, 0); __builtin_amdgcn_s_setprio(0); } while (0)
; #define PG8_WAIT_V(n) asm volatile("s_waitcnt vmcnt(" #n ")" ::: "memory")
; #define PG8_WAIT_L(n) asm volatile("s_waitcnt lgkmcnt(" #n ")" ::: "memory")
; #define PG8_BAR __builtin_amdgcn_s_barrier()
; #define PG8_SCHED __builtin_amdgcn_sched_barrier(0)
; template <class Epi, class Sched>
; __device__ __forceinline__ void gemm_phase(LAS unsigned char* lds, const int tid, const Sched& S, const Epi& E) {
;     ...
;             PG8_LDB(B0, 0, 0); PG8_LDB(B1, 0, 1); PG8_SCHED; PG8_LDA(At, 0, 0); PG8_STAGE(PG8_SA(1, 1), a1 + hA, offA, qA);
;             PG8_WAIT_V(8); PG8_WAIT_L(0); PG8_BAR; PG8_MMA(0, 0, At, B0); PG8_MMA(0, 1, At, B1); PG8_BAR; PG8_SCHED;
;             PG8_LDA(At, 0, 1); PG8_STAGE(PG8_SB(0, 0), b2, oB2, qB2); PG8_STAGE(PG8_SB(0, 1), b2 + hB2, oB2, qB2); PG8_STAGE(PG8_SA(0, 0), a2, oA2, qA2);
;             PG8_WAIT_V(8); PG8_WAIT_L(0); PG8_BAR; PG8_MMA(1, 0, At, B0); PG8_MMA(1, 1, At, B1); PG8_BAR; PG8_SCHED;
.Lk0a_175:
	s_or_b32 vcc_lo, s17, 1
	s_mov_b32 vcc_hi, s21
	s_lshl_b64 s[10:11], vcc, 7
	s_add_u32 s17, s40, s6
	s_addc_u32 vcc_lo, s41, s7
	s_and_b64 s[6:7], exec, s[62:63]
	s_cselect_b32 vcc_hi, s82, vcc_lo
	s_cselect_b32 vcc_lo, s48, s17
	s_add_i32 s17, 0, 0x10000
	v_add_u32_e32 v133, s17, v147
	s_add_i32 s62, 0, 0x14000
	ds_read_b128 v[140:143], v133
	ds_read_b128 v[150:153], v133 offset:1024
	ds_read_b128 v[154:157], v133 offset:2048
	ds_read_b128 v[158:161], v133 offset:3072
	ds_read_b128 v[186:189], v133 offset:16384
	ds_read_b128 v[190:193], v133 offset:17408
	ds_read_b128 v[194:197], v133 offset:18432
	ds_read_b128 v[198:201], v133 offset:19456
	s_add_u32 s6, s68, s10
	s_addc_u32 s7, s16, s11
	s_add_i32 m0, s54, 0xc000
	ds_read_b128 v[202:205], v184
	ds_read_b128 v[206:209], v184 offset:1024
	ds_read_b128 v[210:213], v184 offset:2048
	ds_read_b128 v[214:217], v184 offset:3072
	ds_read_b128 v[218:221], v184 offset:4096
	ds_read_b128 v[222:225], v184 offset:5120
	ds_read_b128 v[226:229], v184 offset:6144
	ds_read_b128 v[230:233], v184 offset:7168
	global_load_lds_dwordx4 v134, s[6:7]
	s_add_u32 s6, s6, s66
	s_addc_u32 s7, s7, s67
	s_add_i32 m0, s54, 0xe000
	s_nop 0
	global_load_lds_dwordx4 v134, s[6:7]
	s_waitcnt vmcnt(16)
	s_waitcnt lgkmcnt(0)
	s_barrier
	s_setprio 1
	s_waitcnt lgkmcnt(0)
	v_mfma_f32_16x16x32_bf16 v[126:129], v[140:143], v[202:205], v[126:129]
	v_mfma_f32_16x16x32_bf16 v[122:125], v[154:157], v[202:205], v[122:125]
	v_mfma_f32_16x16x32_bf16 v[110:113], v[140:143], v[210:213], v[110:113]
	v_mfma_f32_16x16x32_bf16 v[106:109], v[154:157], v[210:213], v[106:109]
	v_mfma_f32_16x16x32_bf16 v[94:97], v[140:143], v[218:221], v[94:97]
	v_mfma_f32_16x16x32_bf16 v[90:93], v[154:157], v[218:221], v[90:93]
	v_mfma_f32_16x16x32_bf16 v[78:81], v[140:143], v[226:229], v[78:81]
	v_mfma_f32_16x16x32_bf16 v[74:77], v[154:157], v[226:229], v[74:77]
	v_mfma_f32_16x16x32_bf16 v[126:129], v[150:153], v[206:209], v[126:129]
	v_mfma_f32_16x16x32_bf16 v[122:125], v[158:161], v[206:209], v[122:125]
	v_mfma_f32_16x16x32_bf16 v[110:113], v[150:153], v[214:217], v[110:113]
	v_mfma_f32_16x16x32_bf16 v[106:109], v[158:161], v[214:217], v[106:109]
	v_mfma_f32_16x16x32_bf16 v[94:97], v[150:153], v[222:225], v[94:97]
	v_mfma_f32_16x16x32_bf16 v[90:93], v[158:161], v[222:225], v[90:93]
	v_mfma_f32_16x16x32_bf16 v[78:81], v[150:153], v[230:233], v[78:81]
	v_mfma_f32_16x16x32_bf16 v[74:77], v[158:161], v[230:233], v[74:77]
	s_setprio 0
	s_setprio 1
	v_mfma_f32_16x16x32_bf16 v[118:121], v[186:189], v[202:205], v[118:121]
	v_mfma_f32_16x16x32_bf16 v[114:117], v[194:197], v[202:205], v[114:117]
	v_mfma_f32_16x16x32_bf16 v[102:105], v[186:189], v[210:213], v[102:105]
	v_mfma_f32_16x16x32_bf16 v[98:101], v[194:197], v[210:213], v[98:101]
	v_mfma_f32_16x16x32_bf16 v[86:89], v[186:189], v[218:221], v[86:89]
	v_mfma_f32_16x16x32_bf16 v[82:85], v[194:197], v[218:221], v[82:85]
	v_mfma_f32_16x16x32_bf16 v[70:73], v[186:189], v[226:229], v[70:73]
	v_mfma_f32_16x16x32_bf16 v[66:69], v[194:197], v[226:229], v[66:69]
	v_mfma_f32_16x16x32_bf16 v[118:121], v[190:193], v[206:209], v[118:121]
	v_mfma_f32_16x16x32_bf16 v[114:117], v[198:201], v[206:209], v[114:117]
	v_mfma_f32_16x16x32_bf16 v[102:105], v[190:193], v[214:217], v[102:105]
	v_mfma_f32_16x16x32_bf16 v[98:101], v[198:201], v[214:217], v[98:101]
	v_mfma_f32_16x16x32_bf16 v[86:89], v[190:193], v[222:225], v[86:89]
	v_mfma_f32_16x16x32_bf16 v[82:85], v[198:201], v[222:225], v[82:85]
	v_mfma_f32_16x16x32_bf16 v[70:73], v[190:193], v[230:233], v[70:73]
	v_mfma_f32_16x16x32_bf16 v[66:69], v[198:201], v[230:233], v[66:69]
	s_setprio 0
	s_barrier
	s_add_i32 s10, s17, s47
	s_ashr_i32 s11, s73, 31
	s_mov_b32 m0, s10
	s_add_u32 s6, s28, s73
	ds_read_b128 v[202:205], v184 offset:16384
	ds_read_b128 v[206:209], v184 offset:17408
	ds_read_b128 v[210:213], v184 offset:18432
	ds_read_b128 v[214:217], v184 offset:19456
	ds_read_b128 v[218:221], v184 offset:20480
	ds_read_b128 v[222:225], v184 offset:21504
	ds_read_b128 v[226:229], v184 offset:22528
	ds_read_b128 v[230:233], v184 offset:23552
	global_load_lds_dwordx4 v0, s[28:29]
	s_addc_u32 s7, s29, s11
	s_add_i32 m0, s10, 0x2000
	v_lshl_add_u64 v[162:163], s[6:7], 0, v[0:1]
	global_load_lds_dwordx4 v0, s[6:7]
	s_ashr_i32 s7, s19, 31
	s_add_u32 s6, s28, s19
	s_addc_u32 s7, s29, s7
	s_add_i32 s10, s62, s47
	s_mov_b32 m0, s10
	v_lshl_add_u64 v[234:235], s[6:7], 0, v[0:1]
	global_load_lds_dwordx4 v0, s[6:7]
	s_add_u32 s6, s6, s73
	s_addc_u32 s7, s7, s11
	s_add_i32 m0, s10, 0x2000
	v_lshl_add_u64 v[236:237], s[6:7], 0, v[0:1]
	global_load_lds_dwordx4 v0, s[6:7]
	s_add_u32 s6, vcc_lo, s64
	v_lshl_add_u64 v[238:239], vcc, 0, v[136:137]
	s_mov_b32 m0, s54
	s_addc_u32 s7, vcc_hi, s65
	global_load_lds_dwordx4 v[238:239], off
	v_lshl_add_u64 v[240:241], s[6:7], 0, v[136:137]
	s_mov_b32 m0, s55
	v_lshl_add_u64 v[144:145], s[28:29], 0, v[0:1]
	global_load_lds_dwordx4 v[240:241], off
	s_waitcnt vmcnt(16)
	s_waitcnt lgkmcnt(0)
	s_barrier
; #define PG8_STAGE(bufoff, gbase, off, q) do { \
;         __builtin_amdgcn_global_load_lds((const unsigned*)((const char*)(gbase) + (off)), (LAS unsigned*)(lds + (bufoff) + ldsw), 16, 0, 0); \
;         __builtin_amdgcn_global_load_lds((const unsigned*)((const char*)(gbase) + (q) + (off)), (LAS unsigned*)(lds + (bufoff) + ldsw + 8192), 16, 0, 0); } while (0)
; #define PG8_LDA(dst, b, h) do { _Pragma("unroll") for (int m = 0; m < 4; ++m) _Pragma("unroll") for (int k = 0; k < 2; ++k) dst[m][k] = *(const LAS bf16x8*)(lds + PG8_SA(b, h) + aoff + m * 2048 + k * 1024); } while (0)
; #define PG8_LDB(dst, b, h) do { _Pragma("unroll") for (int n = 0; n < 2; ++n) _Pragma("unroll") for (int k = 0; k < 2; ++k) dst[n][k] = *(const LAS bf16x8*)(lds + PG8_SB(b, h) + boff + n * 2048 + k * 1024); } while (0)
; #define PG8_MMA(ai, bj, At, Bt) do { __builtin_amdgcn_s_setprio(1); _Pragma("unroll") for (int m = 0; m < 4; ++m) _Pragma("unroll") for (int n = 0; n < 2; ++n) _Pragma("unroll") for (int k = 0; k < 2; ++k) \
;         acc[ai][bj][m][n] = __builtin_amdgcn_mfma_f32_16x16x32_bf16(Bt[n][k], At[m][k], acc[ai][bj][m][n], 0, 0, 0); __builtin_amdgcn_s_setprio(0); } while (0)
; #define PG8_WAIT_V(n) asm volatile("s_waitcnt vmcnt(" #n ")" ::: "memory")
; #define PG8_WAIT_L(n) asm volatile("s_waitcnt lgkmcnt(" #n ")" ::: "memory")
; #define PG8_BAR __builtin_amdgcn_s_barrier()
; #define PG8_SCHED __builtin_amdgcn_sched_barrier(0)
; template <class Epi, class Sched>
; __device__ __forceinline__ void gemm_phase(LAS unsigned char* lds, const int tid, const Sched& S, const Epi& E) {
;     ...
;             PG8_WAIT_V(8); PG8_WAIT_L(0); PG8_BAR; PG8_MMA(1, 0, At, B0); PG8_MMA(1, 1, At, B1); PG8_BAR; PG8_SCHED;
;             PG8_LDB(B0, 1, 0); PG8_LDB(B1, 1, 1); PG8_SCHED; PG8_LDA(At, 1, 0); PG8_STAGE(PG8_SA(0, 1), a2 + hA2, oA2, qA2);
;             PG8_WAIT_V(8); PG8_WAIT_L(0); PG8_BAR; PG8_MMA(0, 0, At, B0); PG8_MMA(0, 1, At, B1); PG8_BAR; PG8_SCHED;
	s_setprio 1
	s_waitcnt lgkmcnt(0)
	v_mfma_f32_16x16x32_bf16 v[62:65], v[140:143], v[202:205], v[62:65]
	v_mfma_f32_16x16x32_bf16 v[58:61], v[154:157], v[202:205], v[58:61]
	v_mfma_f32_16x16x32_bf16 v[46:49], v[140:143], v[210:213], v[46:49]
	v_mfma_f32_16x16x32_bf16 v[42:45], v[154:157], v[210:213], v[42:45]
	v_mfma_f32_16x16x32_bf16 v[30:33], v[140:143], v[218:221], v[30:33]
	v_mfma_f32_16x16x32_bf16 v[26:29], v[154:157], v[218:221], v[26:29]
	v_mfma_f32_16x16x32_bf16 v[14:17], v[140:143], v[226:229], v[14:17]
	v_mfma_f32_16x16x32_bf16 v[10:13], v[154:157], v[226:229], v[10:13]
	v_mfma_f32_16x16x32_bf16 v[62:65], v[150:153], v[206:209], v[62:65]
	v_mfma_f32_16x16x32_bf16 v[58:61], v[158:161], v[206:209], v[58:61]
	v_mfma_f32_16x16x32_bf16 v[46:49], v[150:153], v[214:217], v[46:49]
	v_mfma_f32_16x16x32_bf16 v[42:45], v[158:161], v[214:217], v[42:45]
	v_mfma_f32_16x16x32_bf16 v[30:33], v[150:153], v[222:225], v[30:33]
	v_mfma_f32_16x16x32_bf16 v[26:29], v[158:161], v[222:225], v[26:29]
	v_mfma_f32_16x16x32_bf16 v[14:17], v[150:153], v[230:233], v[14:17]
	v_mfma_f32_16x16x32_bf16 v[10:13], v[158:161], v[230:233], v[10:13]
	s_setprio 0
	s_setprio 1
	v_mfma_f32_16x16x32_bf16 v[54:57], v[186:189], v[202:205], v[54:57]
	v_mfma_f32_16x16x32_bf16 v[50:53], v[194:197], v[202:205], v[50:53]
	v_mfma_f32_16x16x32_bf16 v[38:41], v[186:189], v[210:213], v[38:41]
	v_mfma_f32_16x16x32_bf16 v[34:37], v[194:197], v[210:213], v[34:37]
	v_mfma_f32_16x16x32_bf16 v[22:25], v[186:189], v[218:221], v[22:25]
	v_mfma_f32_16x16x32_bf16 v[18:21], v[194:197], v[218:221], v[18:21]
	v_mfma_f32_16x16x32_bf16 v[6:9], v[186:189], v[226:229], v[6:9]
	v_mfma_f32_16x16x32_bf16 v[2:5], v[194:197], v[226:229], v[2:5]
	v_mfma_f32_16x16x32_bf16 v[54:57], v[190:193], v[206:209], v[54:57]
	v_mfma_f32_16x16x32_bf16 v[50:53], v[198:201], v[206:209], v[50:53]
	v_mfma_f32_16x16x32_bf16 v[38:41], v[190:193], v[214:217], v[38:41]
	v_mfma_f32_16x16x32_bf16 v[34:37], v[198:201], v[214:217], v[34:37]
	v_mfma_f32_16x16x32_bf16 v[22:25], v[190:193], v[222:225], v[22:25]
	v_mfma_f32_16x16x32_bf16 v[18:21], v[198:201], v[222:225], v[18:21]
	v_mfma_f32_16x16x32_bf16 v[6:9], v[190:193], v[230:233], v[6:9]
	v_mfma_f32_16x16x32_bf16 v[2:5], v[198:201], v[230:233], v[2:5]
	s_setprio 0
	s_barrier
	s_add_i32 s10, 0, 0x18000
	s_add_i32 s11, 0, 0x1c000
	ds_read_b128 v[140:143], v133 offset:32768
	ds_read_b128 v[150:153], v133 offset:33792
	ds_read_b128 v[154:157], v133 offset:34816
	ds_read_b128 v[158:161], v133 offset:35840
	ds_read_b128 v[186:189], v133 offset:49152
	ds_read_b128 v[190:193], v133 offset:50176
	ds_read_b128 v[194:197], v133 offset:51200
	ds_read_b128 v[198:201], v133 offset:52224
	s_add_u32 s6, vcc_lo, s58
	s_addc_u32 s7, vcc_hi, s59
	s_mov_b32 m0, s91
	ds_read_b128 v[202:205], v184 offset:32768
	ds_read_b128 v[206:209], v184 offset:33792
	ds_read_b128 v[210:213], v184 offset:34816
	ds_read_b128 v[214:217], v184 offset:35840
	ds_read_b128 v[218:221], v184 offset:36864
	ds_read_b128 v[222:225], v184 offset:37888
	ds_read_b128 v[226:229], v184 offset:38912
	ds_read_b128 v[230:233], v184 offset:39936
	global_load_lds_dwordx4 v136, s[6:7]
	s_add_u32 s6, s6, s64
	s_addc_u32 s7, s7, s65
	s_mov_b32 m0, s93
	s_nop 0
	global_load_lds_dwordx4 v136, s[6:7]
	s_waitcnt vmcnt(8)
	s_waitcnt lgkmcnt(0)
	s_barrier
	s_setprio 1
	s_waitcnt lgkmcnt(0)
	v_mfma_f32_16x16x32_bf16 v[126:129], v[140:143], v[202:205], v[126:129]
	v_mfma_f32_16x16x32_bf16 v[122:125], v[154:157], v[202:205], v[122:125]
	v_mfma_f32_16x16x32_bf16 v[110:113], v[140:143], v[210:213], v[110:113]
	v_mfma_f32_16x16x32_bf16 v[106:109], v[154:157], v[210:213], v[106:109]
	v_mfma_f32_16x16x32_bf16 v[94:97], v[140:143], v[218:221], v[94:97]
	v_mfma_f32_16x16x32_bf16 v[90:93], v[154:157], v[218:221], v[90:93]
	v_mfma_f32_16x16x32_bf16 v[78:81], v[140:143], v[226:229], v[78:81]
	v_mfma_f32_16x16x32_bf16 v[74:77], v[154:157], v[226:229], v[74:77]
	v_mfma_f32_16x16x32_bf16 v[126:129], v[150:153], v[206:209], v[126:129]
	v_mfma_f32_16x16x32_bf16 v[122:125], v[158:161], v[206:209], v[122:125]
	v_mfma_f32_16x16x32_bf16 v[110:113], v[150:153], v[214:217], v[110:113]
	v_mfma_f32_16x16x32_bf16 v[106:109], v[158:161], v[214:217], v[106:109]
	v_mfma_f32_16x16x32_bf16 v[94:97], v[150:153], v[222:225], v[94:97]
	v_mfma_f32_16x16x32_bf16 v[90:93], v[158:161], v[222:225], v[90:93]
	v_mfma_f32_16x16x32_bf16 v[78:81], v[150:153], v[230:233], v[78:81]
	v_mfma_f32_16x16x32_bf16 v[74:77], v[158:161], v[230:233], v[74:77]
	s_setprio 0
	s_setprio 1
	v_mfma_f32_16x16x32_bf16 v[118:121], v[186:189], v[202:205], v[118:121]
	v_mfma_f32_16x16x32_bf16 v[114:117], v[194:197], v[202:205], v[114:117]
	v_mfma_f32_16x16x32_bf16 v[102:105], v[186:189], v[210:213], v[102:105]
	v_mfma_f32_16x16x32_bf16 v[98:101], v[194:197], v[210:213], v[98:101]
	v_mfma_f32_16x16x32_bf16 v[86:89], v[186:189], v[218:221], v[86:89]
	v_mfma_f32_16x16x32_bf16 v[82:85], v[194:197], v[218:221], v[82:85]
	v_mfma_f32_16x16x32_bf16 v[70:73], v[186:189], v[226:229], v[70:73]
	v_mfma_f32_16x16x32_bf16 v[66:69], v[194:197], v[226:229], v[66:69]
	v_mfma_f32_16x16x32_bf16 v[118:121], v[190:193], v[206:209], v[118:121]
	v_mfma_f32_16x16x32_bf16 v[114:117], v[198:201], v[206:209], v[114:117]
	v_mfma_f32_16x16x32_bf16 v[102:105], v[190:193], v[214:217], v[102:105]
	v_mfma_f32_16x16x32_bf16 v[98:101], v[198:201], v[214:217], v[98:101]
	v_mfma_f32_16x16x32_bf16 v[86:89], v[190:193], v[222:225], v[86:89]
	v_mfma_f32_16x16x32_bf16 v[82:85], v[198:201], v[222:225], v[82:85]
	v_mfma_f32_16x16x32_bf16 v[70:73], v[190:193], v[230:233], v[70:73]
	v_mfma_f32_16x16x32_bf16 v[66:69], v[198:201], v[230:233], v[66:69]
	s_setprio 0
	s_barrier
; #define PG8_STAGE(bufoff, gbase, off, q) do { \
;         __builtin_amdgcn_global_load_lds((const unsigned*)((const char*)(gbase) + (off)), (LAS unsigned*)(lds + (bufoff) + ldsw), 16, 0, 0); \
;         __builtin_amdgcn_global_load_lds((const unsigned*)((const char*)(gbase) + (q) + (off)), (LAS unsigned*)(lds + (bufoff) + ldsw + 8192), 16, 0, 0); } while (0)
; #define PG8_LDA(dst, b, h) do { _Pragma("unroll") for (int m = 0; m < 4; ++m) _Pragma("unroll") for (int k = 0; k < 2; ++k) dst[m][k] = *(const LAS bf16x8*)(lds + PG8_SA(b, h) + aoff + m * 2048 + k * 1024); } while (0)
; #define PG8_MMA(ai, bj, At, Bt) do { __builtin_amdgcn_s_setprio(1); _Pragma("unroll") for (int m = 0; m < 4; ++m) _Pragma("unroll") for (int n = 0; n < 2; ++n) _Pragma("unroll") for (int k = 0; k < 2; ++k) \
;         acc[ai][bj][m][n] = __builtin_amdgcn_mfma_f32_16x16x32_bf16(Bt[n][k], At[m][k], acc[ai][bj][m][n], 0, 0, 0); __builtin_amdgcn_s_setprio(0); } while (0)
; #define PG8_WAIT_V(n) asm volatile("s_waitcnt vmcnt(" #n ")" ::: "memory")
; #define PG8_WAIT_L(n) asm volatile("s_waitcnt lgkmcnt(" #n ")" ::: "memory")
; #define PG8_BAR __builtin_amdgcn_s_barrier()
; #define PG8_SCHED __builtin_amdgcn_sched_barrier(0)
; template <class Epi, class Sched>
; __device__ __forceinline__ void gemm_phase(LAS unsigned char* lds, const int tid, const Sched& S, const Epi& E) {
;     ...
;             PG8_LDA(At, 1, 1); PG8_STAGE(PG8_SB(1, 0), b3, oB2, qB2); PG8_STAGE(PG8_SB(1, 1), b3 + hB2, oB2, qB2); PG8_STAGE(PG8_SA(1, 0), a3, oA2, qA2);
;             PG8_WAIT_V(8); PG8_WAIT_L(0); PG8_BAR; PG8_MMA(1, 0, At, B0); PG8_MMA(1, 1, At, B1); PG8_BAR; PG8_SCHED;
;         }
	s_add_i32 s6, s10, s47
	s_add_i32 m0, s6, 0xffffff80
	ds_read_b128 v[202:205], v184 offset:49152
	ds_read_b128 v[206:209], v184 offset:50176
	ds_read_b128 v[210:213], v184 offset:51200
	ds_read_b128 v[214:217], v184 offset:52224
	ds_read_b128 v[218:221], v184 offset:53248
	ds_read_b128 v[222:225], v184 offset:54272
	ds_read_b128 v[226:229], v184 offset:55296
	ds_read_b128 v[230:233], v184 offset:56320
	global_load_lds_dwordx4 v[144:145], off offset:128
	s_add_i32 m0, s6, 0x1f80
	s_add_i32 s6, s11, s47
	global_load_lds_dwordx4 v[162:163], off offset:128
	s_add_i32 m0, s6, 0xffffff80
	s_nop 0
	global_load_lds_dwordx4 v[234:235], off offset:128
	s_add_i32 m0, s6, 0x1f80
	s_nop 0
	global_load_lds_dwordx4 v[236:237], off offset:128
	s_add_i32 m0, s77, 0xffffff80
	s_nop 0
	global_load_lds_dwordx4 v[238:239], off offset:128
	s_add_i32 m0, s88, 0xffffff80
	s_nop 0
	global_load_lds_dwordx4 v[240:241], off offset:128
	s_waitcnt vmcnt(8)
	s_waitcnt lgkmcnt(0)
	s_barrier
	s_setprio 1
	s_waitcnt lgkmcnt(0)
	v_mfma_f32_16x16x32_bf16 v[62:65], v[140:143], v[202:205], v[62:65]
	v_mfma_f32_16x16x32_bf16 v[58:61], v[154:157], v[202:205], v[58:61]
	v_mfma_f32_16x16x32_bf16 v[46:49], v[140:143], v[210:213], v[46:49]
	v_mfma_f32_16x16x32_bf16 v[42:45], v[154:157], v[210:213], v[42:45]
	v_mfma_f32_16x16x32_bf16 v[30:33], v[140:143], v[218:221], v[30:33]
	v_mfma_f32_16x16x32_bf16 v[26:29], v[154:157], v[218:221], v[26:29]
	v_mfma_f32_16x16x32_bf16 v[14:17], v[140:143], v[226:229], v[14:17]
	v_mfma_f32_16x16x32_bf16 v[10:13], v[154:157], v[226:229], v[10:13]
	v_mfma_f32_16x16x32_bf16 v[62:65], v[150:153], v[206:209], v[62:65]
	v_mfma_f32_16x16x32_bf16 v[58:61], v[158:161], v[206:209], v[58:61]
	v_mfma_f32_16x16x32_bf16 v[46:49], v[150:153], v[214:217], v[46:49]
	v_mfma_f32_16x16x32_bf16 v[42:45], v[158:161], v[214:217], v[42:45]
	v_mfma_f32_16x16x32_bf16 v[30:33], v[150:153], v[222:225], v[30:33]
	v_mfma_f32_16x16x32_bf16 v[26:29], v[158:161], v[222:225], v[26:29]
	v_mfma_f32_16x16x32_bf16 v[14:17], v[150:153], v[230:233], v[14:17]
	v_mfma_f32_16x16x32_bf16 v[10:13], v[158:161], v[230:233], v[10:13]
	s_setprio 0
	s_setprio 1
	v_mfma_f32_16x16x32_bf16 v[54:57], v[186:189], v[202:205], v[54:57]
	v_mfma_f32_16x16x32_bf16 v[50:53], v[194:197], v[202:205], v[50:53]
	v_mfma_f32_16x16x32_bf16 v[38:41], v[186:189], v[210:213], v[38:41]
	v_mfma_f32_16x16x32_bf16 v[34:37], v[194:197], v[210:213], v[34:37]
	v_mfma_f32_16x16x32_bf16 v[22:25], v[186:189], v[218:221], v[22:25]
	v_mfma_f32_16x16x32_bf16 v[18:21], v[194:197], v[218:221], v[18:21]
	v_mfma_f32_16x16x32_bf16 v[6:9], v[186:189], v[226:229], v[6:9]
	v_mfma_f32_16x16x32_bf16 v[2:5], v[194:197], v[226:229], v[2:5]
	v_mfma_f32_16x16x32_bf16 v[54:57], v[190:193], v[206:209], v[54:57]
	v_mfma_f32_16x16x32_bf16 v[50:53], v[198:201], v[206:209], v[50:53]
	v_mfma_f32_16x16x32_bf16 v[38:41], v[190:193], v[214:217], v[38:41]
	v_mfma_f32_16x16x32_bf16 v[34:37], v[198:201], v[214:217], v[34:37]
	v_mfma_f32_16x16x32_bf16 v[22:25], v[190:193], v[222:225], v[22:25]
	v_mfma_f32_16x16x32_bf16 v[18:21], v[198:201], v[222:225], v[18:21]
	v_mfma_f32_16x16x32_bf16 v[6:9], v[190:193], v[230:233], v[6:9]
	v_mfma_f32_16x16x32_bf16 v[2:5], v[198:201], v[230:233], v[2:5]
	s_setprio 0
	s_barrier
	s_cmp_ge_i32 s20, s37
	s_cbranch_scc1 .LBB0_177
	s_mov_b32 s17, s20
	s_branch .LBB0_173

; #define PG8_STAGE(bufoff, gbase, off, q) do { \
;         __builtin_amdgcn_global_load_lds((const unsigned*)((const char*)(gbase) + (off)), (LAS unsigned*)(lds + (bufoff) + ldsw), 16, 0, 0); \
;         __builtin_amdgcn_global_load_lds((const unsigned*)((const char*)(gbase) + (q) + (off)), (LAS unsigned*)(lds + (bufoff) + ldsw + 8192), 16, 0, 0); } while (0)
; #define PG8_LDA(dst, b, h) do { _Pragma("unroll") for (int m = 0; m < 4; ++m) _Pragma("unroll") for (int k = 0; k < 2; ++k) dst[m][k] = *(const LAS bf16x8*)(lds + PG8_SA(b, h) + aoff + m * 2048 + k * 1024); } while (0)
; #define PG8_LDB(dst, b, h) do { _Pragma("unroll") for (int n = 0; n < 2; ++n) _Pragma("unroll") for (int k = 0; k < 2; ++k) dst[n][k] = *(const LAS bf16x8*)(lds + PG8_SB(b, h) + boff + n * 2048 + k * 1024); } while (0)
; #define PG8_MMA(ai, bj, At, Bt) do { __builtin_amdgcn_s_setprio(1); _Pragma("unroll") for (int m = 0; m < 4; ++m) _Pragma("unroll") for (int n = 0; n < 2; ++n) _Pragma("unroll") for (int k = 0; k < 2; ++k) \
;         acc[ai][bj][m][n] = __builtin_amdgcn_mfma_f32_16x16x32_bf16(Bt[n][k], At[m][k], acc[ai][bj][m][n], 0, 0, 0); __builtin_amdgcn_s_setprio(0); } while (0)
; #define PG8_WAIT_V(n) asm volatile("s_waitcnt vmcnt(" #n ")" ::: "memory")
; #define PG8_WAIT_L(n) asm volatile("s_waitcnt lgkmcnt(" #n ")" ::: "memory")
; #define PG8_BAR __builtin_amdgcn_s_barrier()
; #define PG8_SCHED __builtin_amdgcn_sched_barrier(0)
; template <class Epi, class Sched>
; __device__ __forceinline__ void gemm_phase(LAS unsigned char* lds, const int tid, const Sched& S, const Epi& E) {
;     ...
;             PG8_LDB(B0, 0, 0); PG8_LDB(B1, 0, 1); PG8_SCHED; PG8_LDA(At, 0, 0); PG8_STAGE(PG8_SA(1, 1), a1 + hA, offA, qA);
;             PG8_WAIT_V(8); PG8_WAIT_L(0); PG8_BAR; PG8_MMA(0, 0, At, B0); PG8_MMA(0, 1, At, B1); PG8_BAR; PG8_SCHED;
;             PG8_LDA(At, 0, 1); PG8_STAGE(PG8_SB(0, 0), b2, oB2, qB2); PG8_STAGE(PG8_SB(0, 1), b2 + hB2, oB2, qB2); PG8_STAGE(PG8_SA(0, 0), a2, oA2, qA2);
;             PG8_WAIT_V(8); PG8_WAIT_L(0); PG8_BAR; PG8_MMA(1, 0, At, B0); PG8_MMA(1, 1, At, B1); PG8_BAR; PG8_SCHED;
.Lk0b_175:
	s_or_b32 vcc_lo, s17, 1
	s_mov_b32 vcc_hi, s21
	s_lshl_b64 s[10:11], vcc, 7
	s_add_u32 s17, s40, s6
	s_addc_u32 vcc_lo, s41, s7
	s_and_b64 s[6:7], exec, s[62:63]
	s_cselect_b32 vcc_hi, s82, vcc_lo
	s_cselect_b32 vcc_lo, s48, s17
	s_add_i32 s17, 0, 0x10000
	v_add_u32_e32 v133, s17, v147
	s_add_i32 s62, 0, 0x14000
	ds_read_b128 v[140:143], v133
	ds_read_b128 v[150:153], v133 offset:1024
	ds_read_b128 v[154:157], v133 offset:2048
	ds_read_b128 v[158:161], v133 offset:3072
	ds_read_b128 v[186:189], v133 offset:16384
	ds_read_b128 v[190:193], v133 offset:17408
	ds_read_b128 v[194:197], v133 offset:18432
	ds_read_b128 v[198:201], v133 offset:19456
	s_add_u32 s6, s68, s10
	s_addc_u32 s7, s16, s11
	s_add_i32 m0, s54, 0xc000
	ds_read_b128 v[202:205], v184
	ds_read_b128 v[206:209], v184 offset:1024
	ds_read_b128 v[210:213], v184 offset:2048
	ds_read_b128 v[214:217], v184 offset:3072
	ds_read_b128 v[218:221], v184 offset:4096
	ds_read_b128 v[222:225], v184 offset:5120
	ds_read_b128 v[226:229], v184 offset:6144
	ds_read_b128 v[230:233], v184 offset:7168
	global_load_lds_dwordx4 v134, s[6:7]
	s_add_u32 s6, s6, s66
	s_addc_u32 s7, s7, s67
	s_add_i32 m0, s54, 0xe000
	s_nop 0
	global_load_lds_dwordx4 v134, s[6:7]
	s_waitcnt vmcnt(24)
	s_waitcnt lgkmcnt(0)
	s_barrier
	s_setprio 1
	s_waitcnt lgkmcnt(0)
	v_mfma_f32_16x16x32_bf16 v[126:129], v[140:143], v[202:205], v[126:129]
	v_mfma_f32_16x16x32_bf16 v[122:125], v[154:157], v[202:205], v[122:125]
	v_mfma_f32_16x16x32_bf16 v[110:113], v[140:143], v[210:213], v[110:113]
	v_mfma_f32_16x16x32_bf16 v[106:109], v[154:157], v[210:213], v[106:109]
	v_mfma_f32_16x16x32_bf16 v[94:97], v[140:143], v[218:221], v[94:97]
	v_mfma_f32_16x16x32_bf16 v[90:93], v[154:157], v[218:221], v[90:93]
	v_mfma_f32_16x16x32_bf16 v[78:81], v[140:143], v[226:229], v[78:81]
	v_mfma_f32_16x16x32_bf16 v[74:77], v[154:157], v[226:229], v[74:77]
	v_mfma_f32_16x16x32_bf16 v[126:129], v[150:153], v[206:209], v[126:129]
	v_mfma_f32_16x16x32_bf16 v[122:125], v[158:161], v[206:209], v[122:125]
	v_mfma_f32_16x16x32_bf16 v[110:113], v[150:153], v[214:217], v[110:113]
	v_mfma_f32_16x16x32_bf16 v[106:109], v[158:161], v[214:217], v[106:109]
	v_mfma_f32_16x16x32_bf16 v[94:97], v[150:153], v[222:225], v[94:97]
	v_mfma_f32_16x16x32_bf16 v[90:93], v[158:161], v[222:225], v[90:93]
	v_mfma_f32_16x16x32_bf16 v[78:81], v[150:153], v[230:233], v[78:81]
	v_mfma_f32_16x16x32_bf16 v[74:77], v[158:161], v[230:233], v[74:77]
	s_setprio 0
	s_setprio 1
	v_mfma_f32_16x16x32_bf16 v[118:121], v[186:189], v[202:205], v[118:121]
	v_mfma_f32_16x16x32_bf16 v[114:117], v[194:197], v[202:205], v[114:117]
	v_mfma_f32_16x16x32_bf16 v[102:105], v[186:189], v[210:213], v[102:105]
	v_mfma_f32_16x16x32_bf16 v[98:101], v[194:197], v[210:213], v[98:101]
	v_mfma_f32_16x16x32_bf16 v[86:89], v[186:189], v[218:221], v[86:89]
	v_mfma_f32_16x16x32_bf16 v[82:85], v[194:197], v[218:221], v[82:85]
	v_mfma_f32_16x16x32_bf16 v[70:73], v[186:189], v[226:229], v[70:73]
	v_mfma_f32_16x16x32_bf16 v[66:69], v[194:197], v[226:229], v[66:69]
	v_mfma_f32_16x16x32_bf16 v[118:121], v[190:193], v[206:209], v[118:121]
	v_mfma_f32_16x16x32_bf16 v[114:117], v[198:201], v[206:209], v[114:117]
	v_mfma_f32_16x16x32_bf16 v[102:105], v[190:193], v[214:217], v[102:105]
	v_mfma_f32_16x16x32_bf16 v[98:101], v[198:201], v[214:217], v[98:101]
	v_mfma_f32_16x16x32_bf16 v[86:89], v[190:193], v[222:225], v[86:89]
	v_mfma_f32_16x16x32_bf16 v[82:85], v[198:201], v[222:225], v[82:85]
	v_mfma_f32_16x16x32_bf16 v[70:73], v[190:193], v[230:233], v[70:73]
	v_mfma_f32_16x16x32_bf16 v[66:69], v[198:201], v[230:233], v[66:69]
	s_setprio 0
	s_barrier
	s_add_i32 s10, s17, s47
	s_ashr_i32 s11, s73, 31
	s_mov_b32 m0, s10
	s_add_u32 s6, s28, s73
	ds_read_b128 v[202:205], v184 offset:16384
	ds_read_b128 v[206:209], v184 offset:17408
	ds_read_b128 v[210:213], v184 offset:18432
	ds_read_b128 v[214:217], v184 offset:19456
	ds_read_b128 v[218:221], v184 offset:20480
	ds_read_b128 v[222:225], v184 offset:21504
	ds_read_b128 v[226:229], v184 offset:22528
	ds_read_b128 v[230:233], v184 offset:23552
	global_load_lds_dwordx4 v0, s[28:29]
	s_addc_u32 s7, s29, s11
	s_add_i32 m0, s10, 0x2000
	v_lshl_add_u64 v[162:163], s[6:7], 0, v[0:1]
	global_load_lds_dwordx4 v0, s[6:7]
	s_ashr_i32 s7, s19, 31
	s_add_u32 s6, s28, s19
	s_addc_u32 s7, s29, s7
	s_add_i32 s10, s62, s47
	s_mov_b32 m0, s10
	v_lshl_add_u64 v[234:235], s[6:7], 0, v[0:1]
	global_load_lds_dwordx4 v0, s[6:7]
	s_add_u32 s6, s6, s73
	s_addc_u32 s7, s7, s11
	s_add_i32 m0, s10, 0x2000
	v_lshl_add_u64 v[236:237], s[6:7], 0, v[0:1]
	global_load_lds_dwordx4 v0, s[6:7]
	s_add_u32 s6, vcc_lo, s64
	v_lshl_add_u64 v[238:239], vcc, 0, v[136:137]
	s_mov_b32 m0, s54
	s_addc_u32 s7, vcc_hi, s65
	global_load_lds_dwordx4 v[238:239], off
	v_lshl_add_u64 v[240:241], s[6:7], 0, v[136:137]
	s_mov_b32 m0, s55
	v_lshl_add_u64 v[144:145], s[28:29], 0, v[0:1]
	global_load_lds_dwordx4 v[240:241], off
	s_waitcnt vmcnt(24)
	s_waitcnt lgkmcnt(0)
	s_barrier
; #define PG8_STAGE(bufoff, gbase, off, q) do { \
;         __builtin_amdgcn_global_load_lds((const unsigned*)((const char*)(gbase) + (off)), (LAS unsigned*)(lds + (bufoff) + ldsw), 16, 0, 0); \
;         __builtin_amdgcn_global_load_lds((const unsigned*)((const char*)(gbase) + (q) + (off)), (LAS unsigned*)(lds + (bufoff) + ldsw + 8192), 16, 0, 0); } while (0)
; #define PG8_LDA(dst, b, h) do { _Pragma("unroll") for (int m = 0; m < 4; ++m) _Pragma("unroll") for (int k = 0; k < 2; ++k) dst[m][k] = *(const LAS bf16x8*)(lds + PG8_SA(b, h) + aoff + m * 2048 + k * 1024); } while (0)
; #define PG8_LDB(dst, b, h) do { _Pragma("unroll") for (int n = 0; n < 2; ++n) _Pragma("unroll") for (int k = 0; k < 2; ++k) dst[n][k] = *(const LAS bf16x8*)(lds + PG8_SB(b, h) + boff + n * 2048 + k * 1024); } while (0)
; #define PG8_MMA(ai, bj, At, Bt) do { __builtin_amdgcn_s_setprio(1); _Pragma("unroll") for (int m = 0; m < 4; ++m) _Pragma("unroll") for (int n = 0; n < 2; ++n) _Pragma("unroll") for (int k = 0; k < 2; ++k) \
;         acc[ai][bj][m][n] = __builtin_amdgcn_mfma_f32_16x16x32_bf16(Bt[n][k], At[m][k], acc[ai][bj][m][n], 0, 0, 0); __builtin_amdgcn_s_setprio(0); } while (0)
; #define PG8_WAIT_V(n) asm volatile("s_waitcnt vmcnt(" #n ")" ::: "memory")
; #define PG8_WAIT_L(n) asm volatile("s_waitcnt lgkmcnt(" #n ")" ::: "memory")
; #define PG8_BAR __builtin_amdgcn_s_barrier()
; #define PG8_SCHED __builtin_amdgcn_sched_barrier(0)
; template <class Epi, class Sched>
; __device__ __forceinline__ void gemm_phase(LAS unsigned char* lds, const int tid, const Sched& S, const Epi& E) {
;     ...
;             PG8_WAIT_V(8); PG8_WAIT_L(0); PG8_BAR; PG8_MMA(1, 0, At, B0); PG8_MMA(1, 1, At, B1); PG8_BAR; PG8_SCHED;
;             PG8_LDB(B0, 1, 0); PG8_LDB(B1, 1, 1); PG8_SCHED; PG8_LDA(At, 1, 0); PG8_STAGE(PG8_SA(0, 1), a2 + hA2, oA2, qA2);
;             PG8_WAIT_V(8); PG8_WAIT_L(0); PG8_BAR; PG8_MMA(0, 0, At, B0); PG8_MMA(0, 1, At, B1); PG8_BAR; PG8_SCHED;
	s_setprio 1
	s_waitcnt lgkmcnt(0)
	v_mfma_f32_16x16x32_bf16 v[62:65], v[140:143], v[202:205], v[62:65]
	v_mfma_f32_16x16x32_bf16 v[58:61], v[154:157], v[202:205], v[58:61]
	v_mfma_f32_16x16x32_bf16 v[46:49], v[140:143], v[210:213], v[46:49]
	v_mfma_f32_16x16x32_bf16 v[42:45], v[154:157], v[210:213], v[42:45]
	v_mfma_f32_16x16x32_bf16 v[30:33], v[140:143], v[218:221], v[30:33]
	v_mfma_f32_16x16x32_bf16 v[26:29], v[154:157], v[218:221], v[26:29]
	v_mfma_f32_16x16x32_bf16 v[14:17], v[140:143], v[226:229], v[14:17]
	v_mfma_f32_16x16x32_bf16 v[10:13], v[154:157], v[226:229], v[10:13]
	v_mfma_f32_16x16x32_bf16 v[62:65], v[150:153], v[206:209], v[62:65]
	v_mfma_f32_16x16x32_bf16 v[58:61], v[158:161], v[206:209], v[58:61]
	v_mfma_f32_16x16x32_bf16 v[46:49], v[150:153], v[214:217], v[46:49]
	v_mfma_f32_16x16x32_bf16 v[42:45], v[158:161], v[214:217], v[42:45]
	v_mfma_f32_16x16x32_bf16 v[30:33], v[150:153], v[222:225], v[30:33]
	v_mfma_f32_16x16x32_bf16 v[26:29], v[158:161], v[222:225], v[26:29]
	v_mfma_f32_16x16x32_bf16 v[14:17], v[150:153], v[230:233], v[14:17]
	v_mfma_f32_16x16x32_bf16 v[10:13], v[158:161], v[230:233], v[10:13]
	s_setprio 0
	s_setprio 1
	v_mfma_f32_16x16x32_bf16 v[54:57], v[186:189], v[202:205], v[54:57]
	v_mfma_f32_16x16x32_bf16 v[50:53], v[194:197], v[202:205], v[50:53]
	v_mfma_f32_16x16x32_bf16 v[38:41], v[186:189], v[210:213], v[38:41]
	v_mfma_f32_16x16x32_bf16 v[34:37], v[194:197], v[210:213], v[34:37]
	v_mfma_f32_16x16x32_bf16 v[22:25], v[186:189], v[218:221], v[22:25]
	v_mfma_f32_16x16x32_bf16 v[18:21], v[194:197], v[218:221], v[18:21]
	v_mfma_f32_16x16x32_bf16 v[6:9], v[186:189], v[226:229], v[6:9]
	v_mfma_f32_16x16x32_bf16 v[2:5], v[194:197], v[226:229], v[2:5]
	v_mfma_f32_16x16x32_bf16 v[54:57], v[190:193], v[206:209], v[54:57]
	v_mfma_f32_16x16x32_bf16 v[50:53], v[198:201], v[206:209], v[50:53]
	v_mfma_f32_16x16x32_bf16 v[38:41], v[190:193], v[214:217], v[38:41]
	v_mfma_f32_16x16x32_bf16 v[34:37], v[198:201], v[214:217], v[34:37]
	v_mfma_f32_16x16x32_bf16 v[22:25], v[190:193], v[222:225], v[22:25]
	v_mfma_f32_16x16x32_bf16 v[18:21], v[198:201], v[222:225], v[18:21]
	v_mfma_f32_16x16x32_bf16 v[6:9], v[190:193], v[230:233], v[6:9]
	v_mfma_f32_16x16x32_bf16 v[2:5], v[198:201], v[230:233], v[2:5]
	s_setprio 0
	s_barrier
	s_add_i32 s10, 0, 0x18000
	s_add_i32 s11, 0, 0x1c000
	ds_read_b128 v[140:143], v133 offset:32768
	ds_read_b128 v[150:153], v133 offset:33792
	ds_read_b128 v[154:157], v133 offset:34816
	ds_read_b128 v[158:161], v133 offset:35840
	ds_read_b128 v[186:189], v133 offset:49152
	ds_read_b128 v[190:193], v133 offset:50176
	ds_read_b128 v[194:197], v133 offset:51200
	ds_read_b128 v[198:201], v133 offset:52224
	s_add_u32 s6, vcc_lo, s58
	s_addc_u32 s7, vcc_hi, s59
	s_mov_b32 m0, s91
	ds_read_b128 v[202:205], v184 offset:32768
	ds_read_b128 v[206:209], v184 offset:33792
	ds_read_b128 v[210:213], v184 offset:34816
	ds_read_b128 v[214:217], v184 offset:35840
	ds_read_b128 v[218:221], v184 offset:36864
	ds_read_b128 v[222:225], v184 offset:37888
	ds_read_b128 v[226:229], v184 offset:38912
	ds_read_b128 v[230:233], v184 offset:39936
	global_load_lds_dwordx4 v136, s[6:7]
	s_add_u32 s6, s6, s64
	s_addc_u32 s7, s7, s65
	s_mov_b32 m0, s93
	s_nop 0
	global_load_lds_dwordx4 v136, s[6:7]
	s_waitcnt vmcnt(8)
	s_waitcnt lgkmcnt(0)
	s_barrier
	s_setprio 1
	s_waitcnt lgkmcnt(0)
	v_mfma_f32_16x16x32_bf16 v[126:129], v[140:143], v[202:205], v[126:129]
	v_mfma_f32_16x16x32_bf16 v[122:125], v[154:157], v[202:205], v[122:125]
	v_mfma_f32_16x16x32_bf16 v[110:113], v[140:143], v[210:213], v[110:113]
	v_mfma_f32_16x16x32_bf16 v[106:109], v[154:157], v[210:213], v[106:109]
	v_mfma_f32_16x16x32_bf16 v[94:97], v[140:143], v[218:221], v[94:97]
	v_mfma_f32_16x16x32_bf16 v[90:93], v[154:157], v[218:221], v[90:93]
	v_mfma_f32_16x16x32_bf16 v[78:81], v[140:143], v[226:229], v[78:81]
	v_mfma_f32_16x16x32_bf16 v[74:77], v[154:157], v[226:229], v[74:77]
	v_mfma_f32_16x16x32_bf16 v[126:129], v[150:153], v[206:209], v[126:129]
	v_mfma_f32_16x16x32_bf16 v[122:125], v[158:161], v[206:209], v[122:125]
	v_mfma_f32_16x16x32_bf16 v[110:113], v[150:153], v[214:217], v[110:113]
	v_mfma_f32_16x16x32_bf16 v[106:109], v[158:161], v[214:217], v[106:109]
	v_mfma_f32_16x16x32_bf16 v[94:97], v[150:153], v[222:225], v[94:97]
	v_mfma_f32_16x16x32_bf16 v[90:93], v[158:161], v[222:225], v[90:93]
	v_mfma_f32_16x16x32_bf16 v[78:81], v[150:153], v[230:233], v[78:81]
	v_mfma_f32_16x16x32_bf16 v[74:77], v[158:161], v[230:233], v[74:77]
	s_setprio 0
	s_setprio 1
	v_mfma_f32_16x16x32_bf16 v[118:121], v[186:189], v[202:205], v[118:121]
	v_mfma_f32_16x16x32_bf16 v[114:117], v[194:197], v[202:205], v[114:117]
	v_mfma_f32_16x16x32_bf16 v[102:105], v[186:189], v[210:213], v[102:105]
	v_mfma_f32_16x16x32_bf16 v[98:101], v[194:197], v[210:213], v[98:101]
	v_mfma_f32_16x16x32_bf16 v[86:89], v[186:189], v[218:221], v[86:89]
	v_mfma_f32_16x16x32_bf16 v[82:85], v[194:197], v[218:221], v[82:85]
	v_mfma_f32_16x16x32_bf16 v[70:73], v[186:189], v[226:229], v[70:73]
	v_mfma_f32_16x16x32_bf16 v[66:69], v[194:197], v[226:229], v[66:69]
	v_mfma_f32_16x16x32_bf16 v[118:121], v[190:193], v[206:209], v[118:121]
	v_mfma_f32_16x16x32_bf16 v[114:117], v[198:201], v[206:209], v[114:117]
	v_mfma_f32_16x16x32_bf16 v[102:105], v[190:193], v[214:217], v[102:105]
	v_mfma_f32_16x16x32_bf16 v[98:101], v[198:201], v[214:217], v[98:101]
	v_mfma_f32_16x16x32_bf16 v[86:89], v[190:193], v[222:225], v[86:89]
	v_mfma_f32_16x16x32_bf16 v[82:85], v[198:201], v[222:225], v[82:85]
	v_mfma_f32_16x16x32_bf16 v[70:73], v[190:193], v[230:233], v[70:73]
	v_mfma_f32_16x16x32_bf16 v[66:69], v[198:201], v[230:233], v[66:69]
	s_setprio 0
	s_barrier
; #define PG8_STAGE(bufoff, gbase, off, q) do { \
;         __builtin_amdgcn_global_load_lds((const unsigned*)((const char*)(gbase) + (off)), (LAS unsigned*)(lds + (bufoff) + ldsw), 16, 0, 0); \
;         __builtin_amdgcn_global_load_lds((const unsigned*)((const char*)(gbase) + (q) + (off)), (LAS unsigned*)(lds + (bufoff) + ldsw + 8192), 16, 0, 0); } while (0)
; #define PG8_LDA(dst, b, h) do { _Pragma("unroll") for (int m = 0; m < 4; ++m) _Pragma("unroll") for (int k = 0; k < 2; ++k) dst[m][k] = *(const LAS bf16x8*)(lds + PG8_SA(b, h) + aoff + m * 2048 + k * 1024); } while (0)
; #define PG8_MMA(ai, bj, At, Bt) do { __builtin_amdgcn_s_setprio(1); _Pragma("unroll") for (int m = 0; m < 4; ++m) _Pragma("unroll") for (int n = 0; n < 2; ++n) _Pragma("unroll") for (int k = 0; k < 2; ++k) \
;         acc[ai][bj][m][n] = __builtin_amdgcn_mfma_f32_16x16x32_bf16(Bt[n][k], At[m][k], acc[ai][bj][m][n], 0, 0, 0); __builtin_amdgcn_s_setprio(0); } while (0)
; #define PG8_WAIT_V(n) asm volatile("s_waitcnt vmcnt(" #n ")" ::: "memory")
; #define PG8_WAIT_L(n) asm volatile("s_waitcnt lgkmcnt(" #n ")" ::: "memory")
; #define PG8_BAR __builtin_amdgcn_s_barrier()
; #define PG8_SCHED __builtin_amdgcn_sched_barrier(0)
; template <class Epi, class Sched>
; __device__ __forceinline__ void gemm_phase(LAS unsigned char* lds, const int tid, const Sched& S, const Epi& E) {
;     ...
;             PG8_LDA(At, 1, 1); PG8_STAGE(PG8_SB(1, 0), b3, oB2, qB2); PG8_STAGE(PG8_SB(1, 1), b3 + hB2, oB2, qB2); PG8_STAGE(PG8_SA(1, 0), a3, oA2, qA2);
;             PG8_WAIT_V(8); PG8_WAIT_L(0); PG8_BAR; PG8_MMA(1, 0, At, B0); PG8_MMA(1, 1, At, B1); PG8_BAR; PG8_SCHED;
;         }
	s_add_i32 s6, s10, s47
	s_add_i32 m0, s6, 0xffffff80
	ds_read_b128 v[202:205], v184 offset:49152
	ds_read_b128 v[206:209], v184 offset:50176
	ds_read_b128 v[210:213], v184 offset:51200
	ds_read_b128 v[214:217], v184 offset:52224
	ds_read_b128 v[218:221], v184 offset:53248
	ds_read_b128 v[222:225], v184 offset:54272
	ds_read_b128 v[226:229], v184 offset:55296
	ds_read_b128 v[230:233], v184 offset:56320
	global_load_lds_dwordx4 v[144:145], off offset:128
	s_add_i32 m0, s6, 0x1f80
	s_add_i32 s6, s11, s47
	global_load_lds_dwordx4 v[162:163], off offset:128
	s_add_i32 m0, s6, 0xffffff80
	s_nop 0
	global_load_lds_dwordx4 v[234:235], off offset:128
	s_add_i32 m0, s6, 0x1f80
	s_nop 0
	global_load_lds_dwordx4 v[236:237], off offset:128
	s_add_i32 m0, s77, 0xffffff80
	s_nop 0
	global_load_lds_dwordx4 v[238:239], off offset:128
	s_add_i32 m0, s88, 0xffffff80
	s_nop 0
	global_load_lds_dwordx4 v[240:241], off offset:128
	s_waitcnt vmcnt(8)
	s_waitcnt lgkmcnt(0)
	s_barrier
	s_setprio 1
	s_waitcnt lgkmcnt(0)
	v_mfma_f32_16x16x32_bf16 v[62:65], v[140:143], v[202:205], v[62:65]
	v_mfma_f32_16x16x32_bf16 v[58:61], v[154:157], v[202:205], v[58:61]
	v_mfma_f32_16x16x32_bf16 v[46:49], v[140:143], v[210:213], v[46:49]
	v_mfma_f32_16x16x32_bf16 v[42:45], v[154:157], v[210:213], v[42:45]
	v_mfma_f32_16x16x32_bf16 v[30:33], v[140:143], v[218:221], v[30:33]
	v_mfma_f32_16x16x32_bf16 v[26:29], v[154:157], v[218:221], v[26:29]
	v_mfma_f32_16x16x32_bf16 v[14:17], v[140:143], v[226:229], v[14:17]
	v_mfma_f32_16x16x32_bf16 v[10:13], v[154:157], v[226:229], v[10:13]
	v_mfma_f32_16x16x32_bf16 v[62:65], v[150:153], v[206:209], v[62:65]
	v_mfma_f32_16x16x32_bf16 v[58:61], v[158:161], v[206:209], v[58:61]
	v_mfma_f32_16x16x32_bf16 v[46:49], v[150:153], v[214:217], v[46:49]
	v_mfma_f32_16x16x32_bf16 v[42:45], v[158:161], v[214:217], v[42:45]
	v_mfma_f32_16x16x32_bf16 v[30:33], v[150:153], v[222:225], v[30:33]
	v_mfma_f32_16x16x32_bf16 v[26:29], v[158:161], v[222:225], v[26:29]
	v_mfma_f32_16x16x32_bf16 v[14:17], v[150:153], v[230:233], v[14:17]
	v_mfma_f32_16x16x32_bf16 v[10:13], v[158:161], v[230:233], v[10:13]
	s_setprio 0
	s_setprio 1
	v_mfma_f32_16x16x32_bf16 v[54:57], v[186:189], v[202:205], v[54:57]
	v_mfma_f32_16x16x32_bf16 v[50:53], v[194:197], v[202:205], v[50:53]
	v_mfma_f32_16x16x32_bf16 v[38:41], v[186:189], v[210:213], v[38:41]
	v_mfma_f32_16x16x32_bf16 v[34:37], v[194:197], v[210:213], v[34:37]
	v_mfma_f32_16x16x32_bf16 v[22:25], v[186:189], v[218:221], v[22:25]
	v_mfma_f32_16x16x32_bf16 v[18:21], v[194:197], v[218:221], v[18:21]
	v_mfma_f32_16x16x32_bf16 v[6:9], v[186:189], v[226:229], v[6:9]
	v_mfma_f32_16x16x32_bf16 v[2:5], v[194:197], v[226:229], v[2:5]
	v_mfma_f32_16x16x32_bf16 v[54:57], v[190:193], v[206:209], v[54:57]
	v_mfma_f32_16x16x32_bf16 v[50:53], v[198:201], v[206:209], v[50:53]
	v_mfma_f32_16x16x32_bf16 v[38:41], v[190:193], v[214:217], v[38:41]
	v_mfma_f32_16x16x32_bf16 v[34:37], v[198:201], v[214:217], v[34:37]
	v_mfma_f32_16x16x32_bf16 v[22:25], v[190:193], v[222:225], v[22:25]
	v_mfma_f32_16x16x32_bf16 v[18:21], v[198:201], v[222:225], v[18:21]
	v_mfma_f32_16x16x32_bf16 v[6:9], v[190:193], v[230:233], v[6:9]
	v_mfma_f32_16x16x32_bf16 v[2:5], v[198:201], v[230:233], v[2:5]
	s_setprio 0
	s_barrier
	s_cmp_ge_i32 s20, s37
	s_cbranch_scc1 .LBB0_177
	s_mov_b32 s17, s20
	s_branch .LBB0_173
